# DA pipelined loop + first P.V operand reads of each MFMA block issued before the block's barrier (V tile already visible)
# speedup vs baseline: 1.0024x; 1.0024x over previous
.LBB0_599:
	s_barrier
	s_setprio 3
	ds_read_b128 v[226:229], v188 offset:45056
	ds_read_b128 v[230:233], v189 offset:40960
	ds_read_b128 v[234:237], v189 offset:45056
	s_waitcnt lgkmcnt(9)
	v_mfma_f32_32x32x16_bf16 v[50:65], v[142:145], v[194:197], v[50:65]
	v_cvt_pk_bf16_f32 v138, v106, v107
	v_add_f32_e32 v242, v98, v99
	v_add_f32_e32 v242, v100, v242
	ds_read_b64_tr_b16 v[210:211], v238 offset:0x1000
	ds_read_b64_tr_b16 v[212:213], v238 offset:0x1800
	s_waitcnt lgkmcnt(9)
	v_mfma_f32_32x32x16_bf16 v[34:49], v[142:145], v[198:201], v[34:49]
	v_cvt_pk_bf16_f32 v139, v108, v109
	v_add_f32_e32 v242, v101, v242
	v_add_f32_e32 v242, v102, v242
	ds_read_b64_tr_b16 v[214:215], v238 offset:0x1200
	ds_read_b64_tr_b16 v[216:217], v238 offset:0x1a00
	s_waitcnt lgkmcnt(9)
	v_mfma_f32_32x32x16_bf16 v[18:33], v[142:145], v[202:205], v[18:33]
	v_cvt_pk_bf16_f32 v140, v110, v111
	v_add_f32_e32 v242, v103, v242
	v_add_f32_e32 v242, v104, v242
	ds_read_b64_tr_b16 v[218:219], v238 offset:0x1400
	ds_read_b64_tr_b16 v[220:221], v238 offset:0x1c00
	s_waitcnt lgkmcnt(9)
	v_mfma_f32_32x32x16_bf16 v[2:17], v[142:145], v[206:209], v[2:17]
	v_cvt_pk_bf16_f32 v141, v112, v113
	v_add_f32_e32 v242, v105, v242
	ds_read_b64_tr_b16 v[222:223], v238 offset:0x1600
	ds_read_b64_tr_b16 v[224:225], v238 offset:0x1e00
	s_waitcnt lgkmcnt(6)
	v_mfma_f32_32x32x16_bf16 v[50:65], v[138:141], v[210:213], v[50:65]
	v_cvt_pk_bf16_f32 v134, v82, v83
	v_add_f32_e32 v242, v106, v242
	v_add_f32_e32 v242, v107, v242
	ds_read_b64_tr_b16 v[194:195], v238 offset:0x2000
	ds_read_b64_tr_b16 v[196:197], v238 offset:0x2800
	s_waitcnt lgkmcnt(6)
	v_mfma_f32_32x32x16_bf16 v[34:49], v[138:141], v[214:217], v[34:49]
	v_cvt_pk_bf16_f32 v135, v84, v85
	v_add_f32_e32 v242, v108, v242
	v_add_f32_e32 v242, v109, v242
	ds_read_b64_tr_b16 v[198:199], v238 offset:0x2200
	ds_read_b64_tr_b16 v[200:201], v238 offset:0x2a00
	s_waitcnt lgkmcnt(6)
	v_mfma_f32_32x32x16_bf16 v[18:33], v[138:141], v[218:221], v[18:33]
	v_cvt_pk_bf16_f32 v136, v86, v87
	v_add_f32_e32 v242, v110, v242
	v_add_f32_e32 v242, v111, v242
	ds_read_b64_tr_b16 v[202:203], v238 offset:0x2400
	ds_read_b64_tr_b16 v[204:205], v238 offset:0x2c00
	s_waitcnt lgkmcnt(6)
	v_mfma_f32_32x32x16_bf16 v[2:17], v[138:141], v[222:225], v[2:17]
	v_cvt_pk_bf16_f32 v137, v88, v89
	v_add_f32_e32 v242, v112, v242
	v_add_f32_e32 v242, v113, v242
	ds_read_b64_tr_b16 v[206:207], v238 offset:0x2600
	ds_read_b64_tr_b16 v[208:209], v238 offset:0x2e00
	s_waitcnt lgkmcnt(6)
	v_mfma_f32_32x32x16_bf16 v[50:65], v[134:137], v[194:197], v[50:65]
	v_cvt_pk_bf16_f32 v130, v90, v91
	v_add_f32_e32 v242, v82, v242
	v_add_f32_e32 v242, v83, v242
	ds_read_b64_tr_b16 v[210:211], v238 offset:0x3000
	ds_read_b64_tr_b16 v[212:213], v238 offset:0x3800
	s_waitcnt lgkmcnt(6)
	v_mfma_f32_32x32x16_bf16 v[34:49], v[134:137], v[198:201], v[34:49]
	v_cvt_pk_bf16_f32 v131, v92, v93
	v_add_f32_e32 v242, v84, v242
	v_add_f32_e32 v242, v85, v242
	ds_read_b64_tr_b16 v[214:215], v238 offset:0x3200
	ds_read_b64_tr_b16 v[216:217], v238 offset:0x3a00
	s_waitcnt lgkmcnt(6)
	v_mfma_f32_32x32x16_bf16 v[18:33], v[134:137], v[202:205], v[18:33]
	v_cvt_pk_bf16_f32 v132, v94, v95
	v_add_f32_e32 v242, v86, v242
	v_add_f32_e32 v242, v87, v242
	ds_read_b64_tr_b16 v[218:219], v238 offset:0x3400
	ds_read_b64_tr_b16 v[220:221], v238 offset:0x3c00
	s_waitcnt lgkmcnt(6)
	v_mfma_f32_32x32x16_bf16 v[2:17], v[134:137], v[206:209], v[2:17]
	v_cvt_pk_bf16_f32 v133, v96, v97
	v_add_f32_e32 v242, v88, v242
	v_add_f32_e32 v242, v89, v242
	ds_read_b64_tr_b16 v[222:223], v238 offset:0x3600
	ds_read_b64_tr_b16 v[224:225], v238 offset:0x3e00
	s_waitcnt lgkmcnt(6)
	v_mfma_f32_32x32x16_bf16 v[50:65], v[130:133], v[210:213], v[50:65]
	v_add_f32_e32 v242, v90, v242
	v_add_f32_e32 v242, v91, v242
	v_add_f32_e32 v242, v92, v242
	v_add_f32_e32 v242, v93, v242
	ds_read_b128 v[82:85], v188 offset:40960
	ds_read_b128 v[194:197], v190 offset:40960
	s_waitcnt lgkmcnt(6)
	v_mfma_f32_32x32x16_bf16 v[34:49], v[130:133], v[214:217], v[34:49]
	v_add_f32_e32 v242, v94, v242
	v_add_f32_e32 v242, v95, v242
	v_add_f32_e32 v242, v96, v242
	v_add_f32_e32 v242, v97, v242
	ds_read_b128 v[198:201], v190 offset:45056
	s_waitcnt lgkmcnt(5)
	v_mfma_f32_32x32x16_bf16 v[18:33], v[130:133], v[218:221], v[18:33]
	v_mov_b32_e32 v243, v242
	s_nop 1
	v_permlane32_swap_b32_e32 v242, v243
	ds_read_b128 v[202:205], v191 offset:40960
	s_waitcnt lgkmcnt(4)
	v_mfma_f32_32x32x16_bf16 v[2:17], v[130:133], v[222:225], v[2:17]
	v_add_f32_e32 v242, v242, v243
	v_fmac_f32_e32 v242, v184, v244
	v_mov_b32_e32 v184, v242
	ds_read_b128 v[206:209], v191 offset:45056
	s_waitcnt lgkmcnt(4)
	v_mfma_f32_32x32x16_bf16 v[98:113], v[82:85], v[126:129], v[66:81]
	v_mfma_f32_32x32x16_bf16 v[82:97], v[226:229], v[126:129], v[66:81]
	v_mfma_f32_32x32x16_bf16 v[98:113], v[230:233], v[122:125], v[98:113]
	v_mfma_f32_32x32x16_bf16 v[82:97], v[234:237], v[122:125], v[82:97]
	s_waitcnt lgkmcnt(3)
	v_mfma_f32_32x32x16_bf16 v[98:113], v[194:197], v[118:121], v[98:113]
	s_waitcnt lgkmcnt(2)
	v_mfma_f32_32x32x16_bf16 v[82:97], v[198:201], v[118:121], v[82:97]
	s_waitcnt lgkmcnt(1)
	v_mfma_f32_32x32x16_bf16 v[98:113], v[202:205], v[114:117], v[98:113]
	s_waitcnt lgkmcnt(0)
	v_mfma_f32_32x32x16_bf16 v[82:97], v[206:209], v[114:117], v[82:97]

.LBB0_610:
	v_exp_f32_e32 v98, v98
	v_exp_f32_e32 v99, v99
	v_exp_f32_e32 v100, v100
	v_exp_f32_e32 v101, v101
	v_exp_f32_e32 v102, v102
	v_exp_f32_e32 v103, v103
	v_exp_f32_e32 v104, v104
	v_exp_f32_e32 v105, v105
	v_exp_f32_e32 v106, v106
	v_exp_f32_e32 v107, v107
	v_exp_f32_e32 v108, v108
	v_exp_f32_e32 v109, v109
	v_exp_f32_e32 v110, v110
	v_exp_f32_e32 v111, v111
	v_exp_f32_e32 v112, v112
	v_exp_f32_e32 v113, v113
	v_exp_f32_e32 v82, v82
	v_exp_f32_e32 v83, v83
	v_exp_f32_e32 v84, v84
	v_exp_f32_e32 v85, v85
	v_exp_f32_e32 v86, v86
	v_exp_f32_e32 v87, v87
	v_exp_f32_e32 v88, v88
	v_exp_f32_e32 v89, v89
	v_exp_f32_e32 v90, v90
	v_exp_f32_e32 v91, v91
	v_exp_f32_e32 v92, v92
	v_exp_f32_e32 v93, v93
	v_exp_f32_e32 v94, v94
	v_exp_f32_e32 v95, v95
	v_exp_f32_e32 v96, v96
	v_exp_f32_e32 v97, v97
	v_add_u32_e32 v247, s75, v193
	s_and_b64 vcc, exec, s[2:3]
	v_cvt_pk_bf16_f32 v142, v98, v99
	v_cvt_pk_bf16_f32 v143, v100, v101
	v_cvt_pk_bf16_f32 v144, v102, v103
	v_cvt_pk_bf16_f32 v145, v104, v105
	ds_read_b64_tr_b16 v[198:199], v247 offset:0
	ds_read_b64_tr_b16 v[200:201], v247 offset:0x800
	ds_read_b64_tr_b16 v[202:203], v247 offset:0x200
	ds_read_b64_tr_b16 v[204:205], v247 offset:0xa00
	ds_read_b64_tr_b16 v[206:207], v247 offset:0x400
	ds_read_b64_tr_b16 v[208:209], v247 offset:0xc00
	ds_read_b64_tr_b16 v[210:211], v247 offset:0x600
	ds_read_b64_tr_b16 v[212:213], v247 offset:0xe00
	s_cbranch_vccnz .LBB0_612
	s_waitcnt vmcnt(1)
.LBB0_612:
	s_barrier
	s_setprio 3
	ds_read_b128 v[230:233], v188 offset:36864
	ds_read_b128 v[234:237], v189 offset:32768
	ds_read_b128 v[238:241], v189 offset:36864
	s_waitcnt lgkmcnt(9)
	v_mfma_f32_32x32x16_bf16 v[50:65], v[142:145], v[198:201], v[50:65]
	v_cvt_pk_bf16_f32 v138, v106, v107
	v_add_f32_e32 v242, v98, v99
	v_add_f32_e32 v242, v100, v242
	ds_read_b64_tr_b16 v[214:215], v247 offset:0x1000
	ds_read_b64_tr_b16 v[216:217], v247 offset:0x1800
	s_waitcnt lgkmcnt(9)
	v_mfma_f32_32x32x16_bf16 v[34:49], v[142:145], v[202:205], v[34:49]
	v_cvt_pk_bf16_f32 v139, v108, v109
	v_add_f32_e32 v242, v101, v242
	v_add_f32_e32 v242, v102, v242
	ds_read_b64_tr_b16 v[218:219], v247 offset:0x1200
	ds_read_b64_tr_b16 v[220:221], v247 offset:0x1a00
	s_waitcnt lgkmcnt(9)
	v_mfma_f32_32x32x16_bf16 v[18:33], v[142:145], v[206:209], v[18:33]
	v_cvt_pk_bf16_f32 v140, v110, v111
	v_add_f32_e32 v242, v103, v242
	v_add_f32_e32 v242, v104, v242
	ds_read_b64_tr_b16 v[222:223], v247 offset:0x1400
	ds_read_b64_tr_b16 v[224:225], v247 offset:0x1c00
	s_waitcnt lgkmcnt(9)
	v_mfma_f32_32x32x16_bf16 v[2:17], v[142:145], v[210:213], v[2:17]
	v_cvt_pk_bf16_f32 v141, v112, v113
	v_add_f32_e32 v242, v105, v242
	ds_read_b64_tr_b16 v[226:227], v247 offset:0x1600
	ds_read_b64_tr_b16 v[228:229], v247 offset:0x1e00
	s_waitcnt lgkmcnt(6)
	v_mfma_f32_32x32x16_bf16 v[50:65], v[138:141], v[214:217], v[50:65]
	v_cvt_pk_bf16_f32 v134, v82, v83
	v_add_f32_e32 v242, v106, v242
	v_add_f32_e32 v242, v107, v242
	ds_read_b64_tr_b16 v[198:199], v247 offset:0x2000
	ds_read_b64_tr_b16 v[200:201], v247 offset:0x2800
	s_waitcnt lgkmcnt(6)
	v_mfma_f32_32x32x16_bf16 v[34:49], v[138:141], v[218:221], v[34:49]
	v_cvt_pk_bf16_f32 v135, v84, v85
	v_add_f32_e32 v242, v108, v242
	v_add_f32_e32 v242, v109, v242
	ds_read_b64_tr_b16 v[202:203], v247 offset:0x2200
	ds_read_b64_tr_b16 v[204:205], v247 offset:0x2a00
	s_waitcnt lgkmcnt(6)
	v_mfma_f32_32x32x16_bf16 v[18:33], v[138:141], v[222:225], v[18:33]
	v_cvt_pk_bf16_f32 v136, v86, v87
	v_add_f32_e32 v242, v110, v242
	v_add_f32_e32 v242, v111, v242
	ds_read_b64_tr_b16 v[206:207], v247 offset:0x2400
	ds_read_b64_tr_b16 v[208:209], v247 offset:0x2c00
	s_waitcnt lgkmcnt(6)
	v_mfma_f32_32x32x16_bf16 v[2:17], v[138:141], v[226:229], v[2:17]
	v_cvt_pk_bf16_f32 v137, v88, v89
	v_add_f32_e32 v242, v112, v242
	v_add_f32_e32 v242, v113, v242
	ds_read_b64_tr_b16 v[210:211], v247 offset:0x2600
	ds_read_b64_tr_b16 v[212:213], v247 offset:0x2e00
	s_waitcnt lgkmcnt(6)
	v_mfma_f32_32x32x16_bf16 v[50:65], v[134:137], v[198:201], v[50:65]
	v_cvt_pk_bf16_f32 v130, v90, v91
	v_add_f32_e32 v242, v82, v242
	v_add_f32_e32 v242, v83, v242
	ds_read_b64_tr_b16 v[214:215], v247 offset:0x3000
	ds_read_b64_tr_b16 v[216:217], v247 offset:0x3800
	s_waitcnt lgkmcnt(6)
	v_mfma_f32_32x32x16_bf16 v[34:49], v[134:137], v[202:205], v[34:49]
	v_cvt_pk_bf16_f32 v131, v92, v93
	v_add_f32_e32 v242, v84, v242
	v_add_f32_e32 v242, v85, v242
	ds_read_b64_tr_b16 v[218:219], v247 offset:0x3200
	ds_read_b64_tr_b16 v[220:221], v247 offset:0x3a00
	s_waitcnt lgkmcnt(6)
	v_mfma_f32_32x32x16_bf16 v[18:33], v[134:137], v[206:209], v[18:33]
	v_cvt_pk_bf16_f32 v132, v94, v95
	v_add_f32_e32 v242, v86, v242
	v_add_f32_e32 v242, v87, v242
	ds_read_b64_tr_b16 v[222:223], v247 offset:0x3400
	ds_read_b64_tr_b16 v[224:225], v247 offset:0x3c00
	s_waitcnt lgkmcnt(6)
	v_mfma_f32_32x32x16_bf16 v[2:17], v[134:137], v[210:213], v[2:17]
	v_cvt_pk_bf16_f32 v133, v96, v97
	v_add_f32_e32 v242, v88, v242
	v_add_f32_e32 v242, v89, v242
	ds_read_b64_tr_b16 v[226:227], v247 offset:0x3600
	ds_read_b64_tr_b16 v[228:229], v247 offset:0x3e00
	s_waitcnt lgkmcnt(6)
	v_mfma_f32_32x32x16_bf16 v[50:65], v[130:133], v[214:217], v[50:65]
	v_add_f32_e32 v242, v90, v242
	v_add_f32_e32 v242, v91, v242
	v_add_f32_e32 v242, v92, v242
	v_add_f32_e32 v242, v93, v242
	ds_read_b128 v[82:85], v188 offset:32768
	ds_read_b128 v[198:201], v190 offset:32768
	s_waitcnt lgkmcnt(6)
	v_mfma_f32_32x32x16_bf16 v[34:49], v[130:133], v[218:221], v[34:49]
	v_add_f32_e32 v242, v94, v242
	v_add_f32_e32 v242, v95, v242
	v_add_f32_e32 v242, v96, v242
	v_add_f32_e32 v242, v97, v242
	ds_read_b128 v[202:205], v190 offset:36864
	s_waitcnt lgkmcnt(5)
	v_mfma_f32_32x32x16_bf16 v[18:33], v[130:133], v[222:225], v[18:33]
	v_mov_b32_e32 v243, v242
	s_nop 1
	v_permlane32_swap_b32_e32 v242, v243
	ds_read_b128 v[206:209], v191 offset:32768
	s_waitcnt lgkmcnt(4)
	v_mfma_f32_32x32x16_bf16 v[2:17], v[130:133], v[226:229], v[2:17]
	v_add_f32_e32 v242, v242, v243
	v_fmac_f32_e32 v242, v184, v194
	v_mov_b32_e32 v184, v242
	ds_read_b128 v[210:213], v191 offset:36864
	s_waitcnt lgkmcnt(4)
	v_mfma_f32_32x32x16_bf16 v[98:113], v[82:85], v[126:129], v[66:81]
	v_mfma_f32_32x32x16_bf16 v[82:97], v[230:233], v[126:129], v[66:81]
	v_mfma_f32_32x32x16_bf16 v[98:113], v[234:237], v[122:125], v[98:113]
	v_mfma_f32_32x32x16_bf16 v[82:97], v[238:241], v[122:125], v[82:97]
	s_waitcnt lgkmcnt(3)
	v_mfma_f32_32x32x16_bf16 v[98:113], v[198:201], v[118:121], v[98:113]
	s_waitcnt lgkmcnt(2)
	v_mfma_f32_32x32x16_bf16 v[82:97], v[202:205], v[118:121], v[82:97]
	s_waitcnt lgkmcnt(1)
	v_mfma_f32_32x32x16_bf16 v[98:113], v[206:209], v[114:117], v[98:113]
	s_waitcnt lgkmcnt(0)
	v_mfma_f32_32x32x16_bf16 v[82:97], v[210:213], v[114:117], v[82:97]
	s_and_b64 vcc, exec, s[6:7]
	s_cbranch_vccnz .LBB0_614
	s_waitcnt vmcnt(1)

.LBB0_625:
	v_mov_b32_e32 v244, v197
	s_add_i32 s96, s96, 2
	s_and_b64 vcc, exec, s[0:1]
	s_cbranch_vccnz .Lrot_da_exit
	s_mov_b32 s0, s12
	s_mov_b32 s12, s75
	s_mov_b32 s75, s74
	s_mov_b32 s74, s0
	v_add_u32_e32 v238, s74, v193
	ds_read_b64_tr_b16 v[194:195], v238 offset:0
	ds_read_b64_tr_b16 v[196:197], v238 offset:0x800
	ds_read_b64_tr_b16 v[198:199], v238 offset:0x200
	ds_read_b64_tr_b16 v[200:201], v238 offset:0xa00
	ds_read_b64_tr_b16 v[202:203], v238 offset:0x400
	ds_read_b64_tr_b16 v[204:205], v238 offset:0xc00
	ds_read_b64_tr_b16 v[206:207], v238 offset:0x600
	ds_read_b64_tr_b16 v[208:209], v238 offset:0xe00
	s_branch .LBB0_599
